# kind-4 FFN weight transposes: bf16 weight stores marked nt (keep the scan operands resident in the infinity cache)
# speedup vs baseline: 1.0073x; 1.0073x over previous
; __device__ __forceinline__ unsigned pk_bf16(float lo, float hi) { f32x2e v = {lo, hi}; bf16x2e b = __builtin_convertvector(v, bf16x2e); return __builtin_bit_cast(unsigned, b); }
; #define LAS __attribute__((address_space(3)))
; __device__ __forceinline__ void tr_item(const float* W, int Ksrc, int N, int k0, int n0, bf16* dst, int ldt, int drow0, int dcol0, LAS float* scr, int lane, const float* nscale = nullptr, const float* kscale = nullptr) {
;     ...
;     for (int i = 0; i < 8; ++i) { const int kk = 8 * i + kr_; const bool ok = (k0 + kk < Ksrc); LAS float* d_ = scr + kk * 33 + 4 * nq_;
;         const float ks_ = (ok && kscale) ? kscale[k0 + kk] : 1.0f;
;         d_[0] = ok ? tv[i].x * ks_ : 0.f; d_[1] = ok ? tv[i].y * ks_ : 0.f; d_[2] = ok ? tv[i].z * ks_ : 0.f; d_[3] = ok ? tv[i].w * ks_ : 0.f; }
;     asm volatile("s_waitcnt lgkmcnt(0)" ::: "memory");
;     const int c = lane & 7;
; #pragma unroll
;     for (int j = 0; j < 4; ++j) { const int n = (lane >> 3) + 8 * j; const LAS float* s = scr + (8 * c) * 33 + n;
;         const float sc = nscale ? nscale[n0 + n] : 1.0f;
;         u32x4 o; o.x = pk_bf16(s[0 * 33] * sc, s[1 * 33] * sc); o.y = pk_bf16(s[2 * 33] * sc, s[3 * 33] * sc); o.z = pk_bf16(s[4 * 33] * sc, s[5 * 33] * sc); o.w = pk_bf16(s[6 * 33] * sc, s[7 * 33] * sc);
;         *(u32x4*)(dst + (size_t)(drow0 + n) * ldt + dcol0 + k0 + 8 * c) = o; }
;     asm volatile("s_waitcnt lgkmcnt(0)" ::: "memory");
.Ltr_noks_g:
	s_or_b64 exec, exec, s[30:31]
	v_add_u32_e32 v70, v35, v37
	s_waitcnt vmcnt(0)
	v_mul_f32_e32 v28, v28, v62
	v_mul_f32_e32 v29, v29, v62
	v_mul_f32_e32 v30, v30, v62
	v_mul_f32_e32 v31, v31, v62
	ds_write2_b32 v70, v28, v29 offset1:1
	ds_write2_b32 v70, v30, v31 offset0:2 offset1:3
	v_mul_f32_e32 v24, v24, v63
	v_mul_f32_e32 v25, v25, v63
	v_mul_f32_e32 v26, v26, v63
	v_mul_f32_e32 v27, v27, v63
	v_add_u32_e32 v71, 0x420, v70
	ds_write2_b32 v71, v24, v25 offset1:1
	ds_write2_b32 v71, v26, v27 offset0:2 offset1:3
	v_mul_f32_e32 v20, v20, v64
	v_mul_f32_e32 v21, v21, v64
	v_mul_f32_e32 v22, v22, v64
	v_mul_f32_e32 v23, v23, v64
	v_add_u32_e32 v71, 0x840, v70
	ds_write2_b32 v71, v20, v21 offset1:1
	ds_write2_b32 v71, v22, v23 offset0:2 offset1:3
	v_mul_f32_e32 v16, v16, v65
	v_mul_f32_e32 v17, v17, v65
	v_mul_f32_e32 v18, v18, v65
	v_mul_f32_e32 v19, v19, v65
	v_add_u32_e32 v71, 0xc60, v70
	ds_write2_b32 v71, v16, v17 offset1:1
	ds_write2_b32 v71, v18, v19 offset0:2 offset1:3
	v_mul_f32_e32 v12, v12, v66
	v_mul_f32_e32 v13, v13, v66
	v_mul_f32_e32 v14, v14, v66
	v_mul_f32_e32 v15, v15, v66
	v_add_u32_e32 v71, 0x1080, v70
	ds_write2_b32 v71, v12, v13 offset1:1
	ds_write2_b32 v71, v14, v15 offset0:2 offset1:3
	v_mul_f32_e32 v8, v8, v67
	v_mul_f32_e32 v9, v9, v67
	v_mul_f32_e32 v10, v10, v67
	v_mul_f32_e32 v11, v11, v67
	v_add_u32_e32 v71, 0x14a0, v70
	ds_write2_b32 v71, v8, v9 offset1:1
	ds_write2_b32 v71, v10, v11 offset0:2 offset1:3
	v_mul_f32_e32 v4, v4, v68
	v_mul_f32_e32 v5, v5, v68
	v_mul_f32_e32 v6, v6, v68
	v_mul_f32_e32 v7, v7, v68
	v_add_u32_e32 v71, 0x18c0, v70
	ds_write2_b32 v71, v4, v5 offset1:1
	ds_write2_b32 v71, v6, v7 offset0:2 offset1:3
	v_mul_f32_e32 v0, v0, v69
	v_mul_f32_e32 v1, v1, v69
	v_mul_f32_e32 v2, v2, v69
	v_mul_f32_e32 v3, v3, v69
	v_add_u32_e32 v71, 0x1ce0, v70
	ds_write2_b32 v71, v0, v1 offset1:1
	ds_write2_b32 v71, v2, v3 offset0:2 offset1:3
	s_waitcnt lgkmcnt(0)
	ds_read_b32 v0, v58
	ds_read_b32 v1, v58 offset:132
	ds_read_b32 v2, v58 offset:264
	ds_read_b32 v3, v58 offset:396
	ds_read_b32 v4, v58 offset:528
	ds_read_b32 v5, v58 offset:660
	ds_read_b32 v6, v58 offset:792
	ds_read_b32 v7, v58 offset:924
	ds_read_b32 v8, v58 offset:32
	ds_read_b32 v9, v58 offset:164
	ds_read_b32 v10, v58 offset:296
	ds_read_b32 v11, v58 offset:428
	ds_read_b32 v12, v58 offset:560
	ds_read_b32 v13, v58 offset:692
	ds_read_b32 v14, v58 offset:824
	ds_read_b32 v15, v58 offset:956
	s_mulk_i32 s14, 0xd400
	s_add_i32 s0, s7, s14
	s_and_b32 s0, s0, 0xffffff00
	s_and_b32 s1, s68, 0x60
	s_or_b32 s0, s1, s0
	s_ashr_i32 s73, s72, 31
	v_mov_b64_e32 v[70:71], s[72:73]
	v_lshl_add_u64 v[70:71], v[70:71], 1, v[44:45]
	s_waitcnt lgkmcnt(8)
	v_cvt_pk_bf16_f32 v80, v0, v1
	v_cvt_pk_bf16_f32 v81, v2, v3
	v_cvt_pk_bf16_f32 v82, v4, v5
	v_cvt_pk_bf16_f32 v83, v6, v7
	v_or_b32_e32 v60, s0, v32
	v_ashrrev_i32_e32 v61, 31, v60
	v_lshlrev_b64 v[60:61], 12, v[60:61]
	v_lshl_add_u64 v[60:61], v[70:71], 0, v[60:61]
	global_store_dwordx4 v[60:61], v[80:83], off nt
	ds_read_b32 v16, v58 offset:64
	ds_read_b32 v17, v58 offset:196
	ds_read_b32 v18, v58 offset:328
	ds_read_b32 v19, v58 offset:460
	ds_read_b32 v20, v58 offset:592
	ds_read_b32 v21, v58 offset:724
	ds_read_b32 v22, v58 offset:856
	ds_read_b32 v23, v58 offset:988
	s_waitcnt lgkmcnt(8)
	v_cvt_pk_bf16_f32 v84, v8, v9
	v_cvt_pk_bf16_f32 v85, v10, v11
	v_cvt_pk_bf16_f32 v86, v12, v13
	v_cvt_pk_bf16_f32 v87, v14, v15
	v_or_b32_e32 v60, s0, v48
	v_ashrrev_i32_e32 v61, 31, v60
	v_lshlrev_b64 v[60:61], 12, v[60:61]
	v_lshl_add_u64 v[60:61], v[70:71], 0, v[60:61]
	global_store_dwordx4 v[60:61], v[84:87], off nt
	ds_read_b32 v24, v58 offset:96
	ds_read_b32 v25, v58 offset:228
	ds_read_b32 v26, v58 offset:360
	ds_read_b32 v27, v58 offset:492
	ds_read_b32 v28, v58 offset:624
	ds_read_b32 v29, v58 offset:756
	ds_read_b32 v30, v58 offset:888
	ds_read_b32 v31, v58 offset:1020
	s_waitcnt lgkmcnt(8)
	v_cvt_pk_bf16_f32 v88, v16, v17
	v_cvt_pk_bf16_f32 v89, v18, v19
	v_cvt_pk_bf16_f32 v90, v20, v21
	v_cvt_pk_bf16_f32 v91, v22, v23
	v_or_b32_e32 v60, s0, v50
	v_ashrrev_i32_e32 v61, 31, v60
	v_lshlrev_b64 v[60:61], 12, v[60:61]
	v_lshl_add_u64 v[60:61], v[70:71], 0, v[60:61]
	global_store_dwordx4 v[60:61], v[88:91], off nt
	s_waitcnt lgkmcnt(0)
	v_cvt_pk_bf16_f32 v92, v24, v25
	v_cvt_pk_bf16_f32 v93, v26, v27
	v_cvt_pk_bf16_f32 v94, v28, v29
	v_cvt_pk_bf16_f32 v95, v30, v31
	v_or_b32_e32 v60, s0, v52
	v_ashrrev_i32_e32 v61, 31, v60
	v_lshlrev_b64 v[60:61], 12, v[60:61]
	v_lshl_add_u64 v[60:61], v[70:71], 0, v[60:61]
	global_store_dwordx4 v[60:61], v[92:95], off nt
	s_add_i32 s8, s8, s19
	s_add_i32 s7, s7, s33
	v_readlane_b32 s0, v253, 48
	s_add_i32 s9, s9, s0
	s_cmpk_lt_i32 s9, 0x1600
	s_cbranch_scc1 .LBB0_330

; __device__ __forceinline__ unsigned pk_bf16(float lo, float hi) { f32x2e v = {lo, hi}; bf16x2e b = __builtin_convertvector(v, bf16x2e); return __builtin_bit_cast(unsigned, b); }
; #define LAS __attribute__((address_space(3)))
; __device__ __forceinline__ void tr_item(const float* W, int Ksrc, int N, int k0, int n0, bf16* dst, int ldt, int drow0, int dcol0, LAS float* scr, int lane, const float* nscale = nullptr, const float* kscale = nullptr) {
;     ...
;     for (int i = 0; i < 8; ++i) { const int kk = 8 * i + kr_; const bool ok = (k0 + kk < Ksrc); LAS float* d_ = scr + kk * 33 + 4 * nq_;
;         const float ks_ = (ok && kscale) ? kscale[k0 + kk] : 1.0f;
;         d_[0] = ok ? tv[i].x * ks_ : 0.f; d_[1] = ok ? tv[i].y * ks_ : 0.f; d_[2] = ok ? tv[i].z * ks_ : 0.f; d_[3] = ok ? tv[i].w * ks_ : 0.f; }
;     asm volatile("s_waitcnt lgkmcnt(0)" ::: "memory");
;     const int c = lane & 7;
; #pragma unroll
;     for (int j = 0; j < 4; ++j) { const int n = (lane >> 3) + 8 * j; const LAS float* s = scr + (8 * c) * 33 + n;
;         const float sc = nscale ? nscale[n0 + n] : 1.0f;
;         u32x4 o; o.x = pk_bf16(s[0 * 33] * sc, s[1 * 33] * sc); o.y = pk_bf16(s[2 * 33] * sc, s[3 * 33] * sc); o.z = pk_bf16(s[4 * 33] * sc, s[5 * 33] * sc); o.w = pk_bf16(s[6 * 33] * sc, s[7 * 33] * sc);
;         *(u32x4*)(dst + (size_t)(drow0 + n) * ldt + dcol0 + k0 + 8 * c) = o; }
;     asm volatile("s_waitcnt lgkmcnt(0)" ::: "memory");
.Ltr_noks_u:
	s_or_b64 exec, exec, s[30:31]
	v_add_u32_e32 v70, v35, v37
	s_waitcnt vmcnt(0)
	v_mul_f32_e32 v28, v28, v62
	v_mul_f32_e32 v29, v29, v62
	v_mul_f32_e32 v30, v30, v62
	v_mul_f32_e32 v31, v31, v62
	ds_write2_b32 v70, v28, v29 offset1:1
	ds_write2_b32 v70, v30, v31 offset0:2 offset1:3
	v_mul_f32_e32 v24, v24, v63
	v_mul_f32_e32 v25, v25, v63
	v_mul_f32_e32 v26, v26, v63
	v_mul_f32_e32 v27, v27, v63
	v_add_u32_e32 v71, 0x420, v70
	ds_write2_b32 v71, v24, v25 offset1:1
	ds_write2_b32 v71, v26, v27 offset0:2 offset1:3
	v_mul_f32_e32 v20, v20, v64
	v_mul_f32_e32 v21, v21, v64
	v_mul_f32_e32 v22, v22, v64
	v_mul_f32_e32 v23, v23, v64
	v_add_u32_e32 v71, 0x840, v70
	ds_write2_b32 v71, v20, v21 offset1:1
	ds_write2_b32 v71, v22, v23 offset0:2 offset1:3
	v_mul_f32_e32 v16, v16, v65
	v_mul_f32_e32 v17, v17, v65
	v_mul_f32_e32 v18, v18, v65
	v_mul_f32_e32 v19, v19, v65
	v_add_u32_e32 v71, 0xc60, v70
	ds_write2_b32 v71, v16, v17 offset1:1
	ds_write2_b32 v71, v18, v19 offset0:2 offset1:3
	v_mul_f32_e32 v12, v12, v66
	v_mul_f32_e32 v13, v13, v66
	v_mul_f32_e32 v14, v14, v66
	v_mul_f32_e32 v15, v15, v66
	v_add_u32_e32 v71, 0x1080, v70
	ds_write2_b32 v71, v12, v13 offset1:1
	ds_write2_b32 v71, v14, v15 offset0:2 offset1:3
	v_mul_f32_e32 v8, v8, v67
	v_mul_f32_e32 v9, v9, v67
	v_mul_f32_e32 v10, v10, v67
	v_mul_f32_e32 v11, v11, v67
	v_add_u32_e32 v71, 0x14a0, v70
	ds_write2_b32 v71, v8, v9 offset1:1
	ds_write2_b32 v71, v10, v11 offset0:2 offset1:3
	v_mul_f32_e32 v4, v4, v68
	v_mul_f32_e32 v5, v5, v68
	v_mul_f32_e32 v6, v6, v68
	v_mul_f32_e32 v7, v7, v68
	v_add_u32_e32 v71, 0x18c0, v70
	ds_write2_b32 v71, v4, v5 offset1:1
	ds_write2_b32 v71, v6, v7 offset0:2 offset1:3
	v_mul_f32_e32 v0, v0, v69
	v_mul_f32_e32 v1, v1, v69
	v_mul_f32_e32 v2, v2, v69
	v_mul_f32_e32 v3, v3, v69
	v_add_u32_e32 v71, 0x1ce0, v70
	ds_write2_b32 v71, v0, v1 offset1:1
	ds_write2_b32 v71, v2, v3 offset0:2 offset1:3
	s_waitcnt lgkmcnt(0)
	ds_read_b32 v0, v58
	ds_read_b32 v1, v58 offset:132
	ds_read_b32 v2, v58 offset:264
	ds_read_b32 v3, v58 offset:396
	ds_read_b32 v4, v58 offset:528
	ds_read_b32 v5, v58 offset:660
	ds_read_b32 v6, v58 offset:792
	ds_read_b32 v7, v58 offset:924
	ds_read_b32 v8, v58 offset:32
	ds_read_b32 v9, v58 offset:164
	ds_read_b32 v10, v58 offset:296
	ds_read_b32 v11, v58 offset:428
	ds_read_b32 v12, v58 offset:560
	ds_read_b32 v13, v58 offset:692
	ds_read_b32 v14, v58 offset:824
	ds_read_b32 v15, v58 offset:956
	s_mulk_i32 s14, 0xd400
	s_add_i32 s0, s7, s14
	s_and_b32 s0, s0, 0xffffff00
	s_and_b32 s1, s42, 0x60
	s_or_b32 s0, s1, s0
	s_bitset1_b32 s0, 7
	s_ashr_i32 s65, s64, 31
	v_mov_b64_e32 v[70:71], s[64:65]
	v_lshl_add_u64 v[70:71], v[70:71], 1, v[40:41]
	s_waitcnt lgkmcnt(8)
	v_cvt_pk_bf16_f32 v80, v0, v1
	v_cvt_pk_bf16_f32 v81, v2, v3
	v_cvt_pk_bf16_f32 v82, v4, v5
	v_cvt_pk_bf16_f32 v83, v6, v7
	v_or_b32_e32 v60, s0, v32
	v_ashrrev_i32_e32 v61, 31, v60
	v_lshlrev_b64 v[60:61], 12, v[60:61]
	v_lshl_add_u64 v[60:61], v[70:71], 0, v[60:61]
	global_store_dwordx4 v[60:61], v[80:83], off nt
	ds_read_b32 v16, v58 offset:64
	ds_read_b32 v17, v58 offset:196
	ds_read_b32 v18, v58 offset:328
	ds_read_b32 v19, v58 offset:460
	ds_read_b32 v20, v58 offset:592
	ds_read_b32 v21, v58 offset:724
	ds_read_b32 v22, v58 offset:856
	ds_read_b32 v23, v58 offset:988
	s_waitcnt lgkmcnt(8)
	v_cvt_pk_bf16_f32 v84, v8, v9
	v_cvt_pk_bf16_f32 v85, v10, v11
	v_cvt_pk_bf16_f32 v86, v12, v13
	v_cvt_pk_bf16_f32 v87, v14, v15
	v_or_b32_e32 v60, s0, v48
	v_ashrrev_i32_e32 v61, 31, v60
	v_lshlrev_b64 v[60:61], 12, v[60:61]
	v_lshl_add_u64 v[60:61], v[70:71], 0, v[60:61]
	global_store_dwordx4 v[60:61], v[84:87], off nt
	ds_read_b32 v24, v58 offset:96
	ds_read_b32 v25, v58 offset:228
	ds_read_b32 v26, v58 offset:360
	ds_read_b32 v27, v58 offset:492
	ds_read_b32 v28, v58 offset:624
	ds_read_b32 v29, v58 offset:756
	ds_read_b32 v30, v58 offset:888
	ds_read_b32 v31, v58 offset:1020
	s_waitcnt lgkmcnt(8)
	v_cvt_pk_bf16_f32 v88, v16, v17
	v_cvt_pk_bf16_f32 v89, v18, v19
	v_cvt_pk_bf16_f32 v90, v20, v21
	v_cvt_pk_bf16_f32 v91, v22, v23
	v_or_b32_e32 v60, s0, v50
	v_ashrrev_i32_e32 v61, 31, v60
	v_lshlrev_b64 v[60:61], 12, v[60:61]
	v_lshl_add_u64 v[60:61], v[70:71], 0, v[60:61]
	global_store_dwordx4 v[60:61], v[88:91], off nt
	s_waitcnt lgkmcnt(0)
	v_cvt_pk_bf16_f32 v92, v24, v25
	v_cvt_pk_bf16_f32 v93, v26, v27
	v_cvt_pk_bf16_f32 v94, v28, v29
	v_cvt_pk_bf16_f32 v95, v30, v31
	v_or_b32_e32 v60, s0, v52
	v_ashrrev_i32_e32 v61, 31, v60
	v_lshlrev_b64 v[60:61], 12, v[60:61]
	v_lshl_add_u64 v[60:61], v[70:71], 0, v[60:61]
	global_store_dwordx4 v[60:61], v[92:95], off nt
	s_add_i32 s8, s8, s19
	s_add_i32 s7, s7, s33
	v_readlane_b32 s0, v253, 48
	s_add_i32 s9, s9, s0
	s_cmpk_lt_i32 s9, 0x1600
	s_cbranch_scc1 .LBB0_351

; #define LAS __attribute__((address_space(3)))
; __device__ __forceinline__ void tr_item(const float* W, int Ksrc, int N, int k0, int n0, bf16* dst, int ldt, int drow0, int dcol0, LAS float* scr, int lane, const float* nscale = nullptr, const float* kscale = nullptr) {
;     f32x4 tv[8]; const int kr_ = lane >> 3, nq_ = lane & 7;
; #pragma unroll
;     for (int i = 0; i < 8; ++i) { const int kk = 8 * i + kr_; const int kr = (k0 + kk < Ksrc) ? (k0 + kk) : (Ksrc - 1); tv[i] = __builtin_nontemporal_load((const f32x4*)(W + (size_t)kr * N + n0 + 4 * nq_)); }
; #pragma unroll
;     for (int i = 0; i < 8; ++i) { const int kk = 8 * i + kr_; const bool ok = (k0 + kk < Ksrc); LAS float* d_ = scr + kk * 33 + 4 * nq_;
;         const float ks_ = (ok && kscale) ? kscale[k0 + kk] : 1.0f;
;         d_[0] = ok ? tv[i].x * ks_ : 0.f; d_[1] = ok ? tv[i].y * ks_ : 0.f; d_[2] = ok ? tv[i].z * ks_ : 0.f; d_[3] = ok ? tv[i].w * ks_ : 0.f; }
;     asm volatile("s_waitcnt lgkmcnt(0)" ::: "memory");
.LBB0_371:
	s_ashr_i32 s6, s1, 31
	s_lshr_b32 s6, s6, 26
	s_add_i32 s7, s1, s6
	s_lshl_b32 s6, s7, 5
	s_and_b32 s34, s7, 0xffffffc0
	s_and_b32 s6, s6, 0xfffff800
	s_add_i32 s8, s11, s0
	v_or_b32_e32 v45, s34, v32
	s_sub_i32 s8, s8, s6
	v_min_i32_e32 v2, 0x15ff, v45
	s_ashr_i32 s9, s8, 31
	v_ashrrev_i32_e32 v3, 31, v2
	v_lshl_add_u64 v[0:1], s[8:9], 2, v[40:41]
	v_lshlrev_b64 v[2:3], 13, v[2:3]
	v_lshl_add_u64 v[2:3], v[0:1], 0, v[2:3]
	global_load_dwordx4 v[28:31], v[2:3], off nt
	v_or_b32_e32 v2, 8, v45
	v_min_i32_e32 v2, 0x15ff, v2
	v_ashrrev_i32_e32 v3, 31, v2
	v_lshlrev_b64 v[2:3], 13, v[2:3]
	v_lshl_add_u64 v[2:3], v[0:1], 0, v[2:3]
	global_load_dwordx4 v[24:27], v[2:3], off nt
	v_or_b32_e32 v2, 16, v45
	v_min_i32_e32 v2, 0x15ff, v2
	v_ashrrev_i32_e32 v3, 31, v2
	v_lshlrev_b64 v[2:3], 13, v[2:3]
	v_lshl_add_u64 v[2:3], v[0:1], 0, v[2:3]
	global_load_dwordx4 v[20:23], v[2:3], off nt
	v_or_b32_e32 v2, 24, v45
	v_min_i32_e32 v2, 0x15ff, v2
	v_ashrrev_i32_e32 v3, 31, v2
	v_lshlrev_b64 v[2:3], 13, v[2:3]
	v_lshl_add_u64 v[2:3], v[0:1], 0, v[2:3]
	global_load_dwordx4 v[16:19], v[2:3], off nt
	v_or_b32_e32 v2, 32, v45
	v_min_i32_e32 v2, 0x15ff, v2
	v_ashrrev_i32_e32 v3, 31, v2
	v_lshlrev_b64 v[2:3], 13, v[2:3]
	v_lshl_add_u64 v[2:3], v[0:1], 0, v[2:3]
	global_load_dwordx4 v[12:15], v[2:3], off nt
	v_or_b32_e32 v2, 40, v45
	v_min_i32_e32 v2, 0x15ff, v2
	v_ashrrev_i32_e32 v3, 31, v2
	v_lshlrev_b64 v[2:3], 13, v[2:3]
	v_lshl_add_u64 v[2:3], v[0:1], 0, v[2:3]
	global_load_dwordx4 v[8:11], v[2:3], off nt
	v_or_b32_e32 v2, 48, v45
	v_min_i32_e32 v2, 0x15ff, v2
	v_ashrrev_i32_e32 v3, 31, v2
	v_lshlrev_b64 v[2:3], 13, v[2:3]
	v_lshl_add_u64 v[2:3], v[0:1], 0, v[2:3]
	global_load_dwordx4 v[4:7], v[2:3], off nt
	v_or_b32_e32 v2, 56, v45
	v_min_i32_e32 v2, 0x15ff, v2
	v_ashrrev_i32_e32 v3, 31, v2
	v_lshlrev_b64 v[2:3], 13, v[2:3]
	v_lshl_add_u64 v[0:1], v[0:1], 0, v[2:3]
	global_load_dwordx4 v[0:3], v[0:1], off nt
	v_cmp_gt_i32_e32 vcc, s15, v45
	v_add_u32_e32 v45, v35, v37
	s_sub_i32 s6, s11, s6
	s_ashr_i32 s35, s34, 31
	s_add_i32 s1, s1, s14
	s_add_i32 s0, s0, s19
	s_cmpk_lt_i32 s1, 0x1600
	s_waitcnt vmcnt(0) lgkmcnt(0)
	v_cndmask_b32_e32 v28, 0, v28, vcc
	v_cndmask_b32_e32 v29, 0, v29, vcc
	ds_write2_b32 v45, v28, v29 offset1:1
	v_cndmask_b32_e32 v28, 0, v30, vcc
	v_cndmask_b32_e32 v29, 0, v31, vcc
	ds_write2_b32 v45, v28, v29 offset0:2 offset1:3
	v_or_b32_e32 v28, s34, v48
	v_cmp_gt_i32_e32 vcc, s15, v28
	v_add_u32_e32 v28, 0x420, v45
	s_nop 0
	v_cndmask_b32_e32 v24, 0, v24, vcc
	v_cndmask_b32_e32 v25, 0, v25, vcc
	ds_write2_b32 v28, v24, v25 offset1:1
	v_cndmask_b32_e32 v24, 0, v26, vcc
	v_cndmask_b32_e32 v25, 0, v27, vcc
	v_add_u32_e32 v26, 0x428, v45
	ds_write2_b32 v26, v24, v25 offset1:1
	v_or_b32_e32 v24, s34, v50
	v_cmp_gt_i32_e32 vcc, s15, v24
	v_add_u32_e32 v24, 0x840, v45
	s_nop 0
	v_cndmask_b32_e32 v20, 0, v20, vcc
	v_cndmask_b32_e32 v21, 0, v21, vcc
	ds_write2_b32 v24, v20, v21 offset1:1
	v_cndmask_b32_e32 v20, 0, v22, vcc
	v_cndmask_b32_e32 v21, 0, v23, vcc
	v_add_u32_e32 v22, 0x848, v45
	ds_write2_b32 v22, v20, v21 offset1:1
	v_or_b32_e32 v20, s34, v52
	v_cmp_gt_i32_e32 vcc, s15, v20
	v_add_u32_e32 v20, 0xc60, v45
	s_nop 0
	v_cndmask_b32_e32 v16, 0, v16, vcc
	v_cndmask_b32_e32 v17, 0, v17, vcc
	ds_write2_b32 v20, v16, v17 offset1:1
	v_cndmask_b32_e32 v16, 0, v18, vcc
	v_cndmask_b32_e32 v17, 0, v19, vcc
	v_add_u32_e32 v18, 0xc68, v45
	ds_write2_b32 v18, v16, v17 offset1:1
	v_or_b32_e32 v16, s34, v54
	v_cmp_gt_i32_e32 vcc, s15, v16
	v_add_u32_e32 v16, 0x1080, v45
	s_nop 0
	v_cndmask_b32_e32 v12, 0, v12, vcc
	v_cndmask_b32_e32 v13, 0, v13, vcc
	ds_write2_b32 v16, v12, v13 offset1:1
	v_cndmask_b32_e32 v12, 0, v14, vcc
	v_cndmask_b32_e32 v13, 0, v15, vcc
	v_add_u32_e32 v14, 0x1088, v45
	ds_write2_b32 v14, v12, v13 offset1:1
	v_or_b32_e32 v12, s34, v55
	v_cmp_gt_i32_e32 vcc, s15, v12
	v_add_u32_e32 v12, 0x14a0, v45
	s_nop 0
	v_cndmask_b32_e32 v8, 0, v8, vcc
	v_cndmask_b32_e32 v9, 0, v9, vcc
	ds_write2_b32 v12, v8, v9 offset1:1
	v_cndmask_b32_e32 v8, 0, v10, vcc
	v_cndmask_b32_e32 v9, 0, v11, vcc
	v_add_u32_e32 v10, 0x14a8, v45
	ds_write2_b32 v10, v8, v9 offset1:1
	v_or_b32_e32 v8, s34, v56
	v_cmp_gt_i32_e32 vcc, s15, v8
	v_add_u32_e32 v8, 0x18c0, v45
	s_nop 0
	v_cndmask_b32_e32 v4, 0, v4, vcc
	v_cndmask_b32_e32 v5, 0, v5, vcc
	ds_write2_b32 v8, v4, v5 offset1:1
	v_cndmask_b32_e32 v4, 0, v6, vcc
	v_cndmask_b32_e32 v5, 0, v7, vcc
	v_add_u32_e32 v6, 0x18c8, v45
	ds_write2_b32 v6, v4, v5 offset1:1
	v_or_b32_e32 v4, s34, v57
	v_cmp_gt_i32_e32 vcc, s15, v4
	v_add_u32_e32 v4, 0x1ce0, v45
	v_add_u32_e32 v8, s6, v44
	v_cndmask_b32_e32 v0, 0, v0, vcc
	v_cndmask_b32_e32 v1, 0, v1, vcc
	ds_write2_b32 v4, v0, v1 offset1:1
	v_cndmask_b32_e32 v0, 0, v2, vcc
	v_cndmask_b32_e32 v1, 0, v3, vcc
	v_add_u32_e32 v2, 0x1ce8, v45
	ds_write2_b32 v2, v0, v1 offset1:1
	s_waitcnt lgkmcnt(0)
; __device__ __forceinline__ unsigned pk_bf16(float lo, float hi) { f32x2e v = {lo, hi}; bf16x2e b = __builtin_convertvector(v, bf16x2e); return __builtin_bit_cast(unsigned, b); }
; #define LAS __attribute__((address_space(3)))
; __device__ __forceinline__ void tr_item(const float* W, int Ksrc, int N, int k0, int n0, bf16* dst, int ldt, int drow0, int dcol0, LAS float* scr, int lane, const float* nscale = nullptr, const float* kscale = nullptr) {
;     ...
;     const int c = lane & 7;
; #pragma unroll
;     for (int j = 0; j < 4; ++j) { const int n = (lane >> 3) + 8 * j; const LAS float* s = scr + (8 * c) * 33 + n;
;         const float sc = nscale ? nscale[n0 + n] : 1.0f;
;         u32x4 o; o.x = pk_bf16(s[0 * 33] * sc, s[1 * 33] * sc); o.y = pk_bf16(s[2 * 33] * sc, s[3 * 33] * sc); o.z = pk_bf16(s[4 * 33] * sc, s[5 * 33] * sc); o.w = pk_bf16(s[6 * 33] * sc, s[7 * 33] * sc);
;         *(u32x4*)(dst + (size_t)(drow0 + n) * ldt + dcol0 + k0 + 8 * c) = o; }
;     asm volatile("s_waitcnt lgkmcnt(0)" ::: "memory");
	ds_read_b32 v0, v58
	ds_read_b32 v1, v58 offset:132
	v_lshl_add_u64 v[4:5], s[34:35], 1, v[42:43]
	v_add_u32_e32 v44, s19, v44
	s_waitcnt lgkmcnt(0)
	v_cvt_pk_bf16_f32 v0, v0, v1
	ds_read_b32 v1, v58 offset:264
	ds_read_b32 v2, v58 offset:396
	s_waitcnt lgkmcnt(0)
	v_cvt_pk_bf16_f32 v1, v1, v2
	ds_read_b32 v2, v58 offset:528
	ds_read_b32 v3, v58 offset:660
	s_waitcnt lgkmcnt(0)
	v_cvt_pk_bf16_f32 v2, v2, v3
	ds_read_b32 v3, v58 offset:792
	ds_read_b32 v6, v58 offset:924
	s_waitcnt lgkmcnt(0)
	v_cvt_pk_bf16_f32 v3, v3, v6
	v_add_u32_e32 v6, 0xffffc000, v8
	v_mad_i64_i32 v[6:7], s[6:7], v6, s28, v[4:5]
	global_store_dwordx4 v[6:7], v[0:3], off nt
	ds_read_b32 v0, v58 offset:32
	ds_read_b32 v1, v58 offset:164
	s_waitcnt lgkmcnt(0)
	v_cvt_pk_bf16_f32 v0, v0, v1
	ds_read_b32 v1, v58 offset:296
	ds_read_b32 v2, v58 offset:428
	s_waitcnt lgkmcnt(0)
	v_cvt_pk_bf16_f32 v1, v1, v2
	ds_read_b32 v2, v58 offset:560
	ds_read_b32 v3, v58 offset:692
	s_waitcnt lgkmcnt(0)
	v_cvt_pk_bf16_f32 v2, v2, v3
	ds_read_b32 v3, v58 offset:824
	ds_read_b32 v6, v58 offset:956
	s_waitcnt lgkmcnt(0)
	v_cvt_pk_bf16_f32 v3, v3, v6
	v_add_u32_e32 v6, 0xffffc008, v8
	v_mad_i64_i32 v[6:7], s[6:7], v6, s28, v[4:5]
	global_store_dwordx4 v[6:7], v[0:3], off nt
	ds_read_b32 v0, v58 offset:64
	ds_read_b32 v1, v58 offset:196
	s_waitcnt lgkmcnt(0)
	v_cvt_pk_bf16_f32 v0, v0, v1
	ds_read_b32 v1, v58 offset:328
	ds_read_b32 v2, v58 offset:460
	s_waitcnt lgkmcnt(0)
	v_cvt_pk_bf16_f32 v1, v1, v2
	ds_read_b32 v2, v58 offset:592
	ds_read_b32 v3, v58 offset:724
	s_waitcnt lgkmcnt(0)
	v_cvt_pk_bf16_f32 v2, v2, v3
	ds_read_b32 v3, v58 offset:856
	ds_read_b32 v6, v58 offset:988
	s_waitcnt lgkmcnt(0)
	v_cvt_pk_bf16_f32 v3, v3, v6
	v_add_u32_e32 v6, 0xffffc010, v8
	v_mad_i64_i32 v[6:7], s[6:7], v6, s28, v[4:5]
	global_store_dwordx4 v[6:7], v[0:3], off nt
	ds_read_b32 v0, v58 offset:96
	ds_read_b32 v1, v58 offset:228
	s_waitcnt lgkmcnt(0)
	v_cvt_pk_bf16_f32 v0, v0, v1
	ds_read_b32 v1, v58 offset:360
	ds_read_b32 v2, v58 offset:492
	s_waitcnt lgkmcnt(0)
	v_cvt_pk_bf16_f32 v1, v1, v2
	ds_read_b32 v2, v58 offset:624
	ds_read_b32 v3, v58 offset:756
	s_waitcnt lgkmcnt(0)
	v_cvt_pk_bf16_f32 v2, v2, v3
	ds_read_b32 v3, v58 offset:888
	ds_read_b32 v6, v58 offset:1020
	s_waitcnt lgkmcnt(0)
	v_cvt_pk_bf16_f32 v3, v3, v6
	v_add_u32_e32 v6, 0xffffc018, v8
	v_mad_i64_i32 v[4:5], s[6:7], v6, s28, v[4:5]
	global_store_dwordx4 v[4:5], v[0:3], off nt
	s_waitcnt lgkmcnt(0)
	s_cbranch_scc1 .LBB0_371
	s_branch .LBB0_326
